# attn loop: ring-offset SGPR rotation moved ahead of the loop-back barrier
# speedup vs baseline: 1.0084x; 1.0007x over previous
; #define PHASE_M(j) do { SBAR(); __builtin_amdgcn_s_setprio(2); if ((j) > 0) pv_d0(o, vb0 + bV, pa0, pa1, pa2, pa3); qkt(p0, p1, Kb + bK, qr, negm, r32, hi); __builtin_amdgcn_s_setprio(0); SBAR(); __syncthreads(); } while (0)
; #define PHASE_V(j, slot) do { softmaxT(p0, p1, mref, negm, l_reg, alpha, pa0, pa1, pa2, pa3); RESC(alpha); \
;     { const int s_ = (j) + 1 + trail; if (s_ < NT) { asm volatile("s_waitcnt vmcnt(3)" ::: "memory"); SWRITE_AT(trail ? bNN : bN, slot); const int s2_ = s_ + 2; SLOAD(slot, s2_ < NT ? s2_ : NT - 1); } } \
;     __syncthreads(); bV = bK; bK = bN; bN = bNN; bNN = bV; } while (0)
; __device__ __forceinline__ void softmaxT(f32x16& p0, f32x16& p1, float& mref, f32x16& negm, float& l_reg, float& alpha, bf16x8& pa0, bf16x8& pa1, bf16x8& pa2, bf16x8& pa3) {
;     ...
;   { float s0 = p0[0] + p1[0], s1 = p0[1] + p1[1], s2 = p0[2] + p1[2], s3 = p0[3] + p1[3];
; #pragma unroll
;     for (int r = 4; r < 16; r += 4) { s0 += p0[r] + p1[r]; s1 += p0[r + 1] + p1[r + 1]; s2 += p0[r + 2] + p1[r + 2]; s3 += p0[r + 3] + p1[r + 3]; }
;     l_reg += (s0 + s1) + (s2 + s3); }
; __device__ __forceinline__ void attn_unit(const bf16_t* __restrict__ Qb, bool rope_q, int tq0, const bf16_t* __restrict__ KVh, const bf16_t* __restrict__ KR,
;                                           int ctx_row0, int lat_row0, int NT, bf16_t* __restrict__ Ob, LAS unsigned char* lds, int wave_s) {
;     ...
;   for (int j = 0; j < NT; j += 2) {
;     PHASE_M(j); PHASE_V(j, 1);
;     PHASE_M(j + 1); PHASE_V(j + 1, 0);
;   }
.LBB0_538:
	v_pk_add_f32 v[222:223], v[66:67], v[222:223]
	v_pk_add_f32 v[224:225], v[68:69], v[224:225]
	v_pk_add_f32 v[226:227], v[70:71], v[226:227]
	v_pk_add_f32 v[228:229], v[72:73], v[228:229]
	v_pk_add_f32 v[230:231], v[74:75], v[230:231]
	v_pk_add_f32 v[232:233], v[76:77], v[232:233]
	v_pk_add_f32 v[234:235], v[78:79], v[234:235]
	v_pk_add_f32 v[236:237], v[80:81], v[236:237]
	v_pk_add_f32 v[222:223], v[222:223], v[224:225]
	v_pk_add_f32 v[226:227], v[226:227], v[228:229]
	v_pk_add_f32 v[230:231], v[230:231], v[232:233]
	v_pk_add_f32 v[234:235], v[234:235], v[236:237]
	v_pk_add_f32 v[222:223], v[222:223], v[226:227]
	v_pk_add_f32 v[230:231], v[230:231], v[234:235]
	v_pk_add_f32 v[222:223], v[222:223], v[230:231]
	v_add_f32_e32 v222, v222, v223
	s_add_i32 s11, s11, 2
	v_add_f32_e32 v157, v157, v222
	s_and_b64 vcc, exec, s[0:1]
	v_add_u32_e32 v174, s10, v156
	ds_read_b64_tr_b16 v[66:67], v174 offset:0
	ds_read_b64_tr_b16 v[68:69], v174 offset:0x800
	ds_read_b64_tr_b16 v[158:159], v174 offset:0x200
	ds_read_b64_tr_b16 v[160:161], v174 offset:0xa00
	s_mov_b32 s0, s10
	s_mov_b32 s10, s5
	s_mov_b32 s5, s22
	s_mov_b32 s22, s0
	s_waitcnt lgkmcnt(4)
	s_barrier
	s_cbranch_vccnz .LBB0_542
	s_setprio 2
	s_branch .Lmy_attn_m1
